# barrier polls keep two staggered loads in flight (faster release detection); otherwise as the division-rewrite version
# speedup vs baseline: 1.0031x; 1.0005x over previous
.Lb3_poll_0:
	s_movk_i32 m0, 0x3fff
	global_load_dword v5, v3, s[98:99] sc1
	s_sleep 5
.Lb3_p_0:
	global_load_dword v9, v3, s[98:99] sc1
	s_waitcnt vmcnt(1)
	v_readfirstlane_b32 vcc_lo, v5
	s_cmp_ge_u32 vcc_lo, s100
	s_cbranch_scc1 .Lb3_pok_0
	global_load_dword v5, v3, s[98:99] sc1
	s_waitcnt vmcnt(1)
	v_readfirstlane_b32 vcc_lo, v9
	s_cmp_ge_u32 vcc_lo, s100
	s_cbranch_scc1 .Lb3_pok_0
	s_sub_u32 m0, m0, 1
	s_cmp_eq_u32 m0, 0
	s_cbranch_scc0 .Lb3_p_0

.LBB0_226:
	s_getreg_b32 s0, hwreg(HW_REG_XCC_ID, 0, 4)
	s_and_b32 s9, s0, 15
	s_waitcnt vmcnt(0)
	s_waitcnt vmcnt(0)
	s_barrier
	s_and_saveexec_b64 s[0:1], s[52:53]
	v_readlane_b32 s24, v255, 22
	s_cbranch_execz .LBB0_278
	v_readlane_b32 s98, v253, 2
	v_readlane_b32 s99, v253, 3
	s_nop 0
	s_add_u32 s98, s98, 0x7c000
	s_addc_u32 s99, s99, 0
	s_and_b32 vcc_hi, s2, 7
	s_sub_u32 vcc_lo, 7, vcc_hi
	s_add_u32 vcc_lo, vcc_lo, s3
	s_lshr_b32 vcc_lo, vcc_lo, 3
	s_lshl_b32 vcc_hi, vcc_hi, 8
	s_add_u32 vcc_hi, vcc_hi, 0x8000
	s_cmp_lt_u32 s101, 10
	s_cselect_b32 m0, 0, 0x800
	s_add_u32 vcc_hi, vcc_hi, m0
	v_mov_b32_e32 v3, vcc_hi
	v_mov_b32_e32 v4, 1
	s_mov_b32 vcc_hi, vcc_lo
	s_waitcnt vmcnt(0) lgkmcnt(0)
	global_atomic_add v5, v3, v4, s[98:99] sc0
	s_waitcnt vmcnt(0)
	v_readfirstlane_b32 vcc_lo, v5
	s_add_i32 vcc_lo, vcc_lo, 1
	s_cmp_ge_u32 vcc_lo, vcc_hi
	s_cbranch_scc1 .Lb3_pok_1
	s_movk_i32 m0, 0x3fff
	global_load_dword v5, v3, s[98:99] sc1
	s_sleep 5
.Lb3_p_1:
	global_load_dword v9, v3, s[98:99] sc1
	s_waitcnt vmcnt(1)
	v_readfirstlane_b32 vcc_lo, v5
	s_cmp_ge_u32 vcc_lo, vcc_hi
	s_cbranch_scc1 .Lb3_pok_1
	global_load_dword v5, v3, s[98:99] sc1
	s_waitcnt vmcnt(1)
	v_readfirstlane_b32 vcc_lo, v9
	s_cmp_ge_u32 vcc_lo, vcc_hi
	s_cbranch_scc1 .Lb3_pok_1
	s_sub_u32 m0, m0, 1
	s_cmp_eq_u32 m0, 0
	s_cbranch_scc0 .Lb3_p_1

.LBB0_292:
	s_getreg_b32 s0, hwreg(HW_REG_XCC_ID, 0, 4)
	s_and_b32 s9, s0, 15
	s_waitcnt vmcnt(0)
	v_readlane_b32 s52, v253, 4
	v_readlane_b32 s53, v253, 5
	s_barrier
	s_and_saveexec_b64 s[0:1], s[52:53]
	v_readlane_b32 s54, v255, 8
	v_readlane_b32 s55, v255, 9
	s_cbranch_execz .LBB0_344
	v_readlane_b32 s98, v253, 2
	v_readlane_b32 s99, v253, 3
	s_nop 0
	s_add_u32 s98, s98, 0x7c000
	s_addc_u32 s99, s99, 0
	s_and_b32 vcc_hi, s2, 7
	s_sub_u32 vcc_lo, 7, vcc_hi
	s_add_u32 vcc_lo, vcc_lo, s3
	s_lshr_b32 vcc_lo, vcc_lo, 3
	s_lshl_b32 vcc_hi, vcc_hi, 8
	s_add_u32 vcc_hi, vcc_hi, 0x9000
	s_cmp_lt_u32 s101, 10
	s_cselect_b32 m0, 0, 0x800
	s_add_u32 vcc_hi, vcc_hi, m0
	v_mov_b32_e32 v3, vcc_hi
	v_mov_b32_e32 v4, 1
	s_mov_b32 vcc_hi, vcc_lo
	s_waitcnt vmcnt(0) lgkmcnt(0)
	global_atomic_add v5, v3, v4, s[98:99] sc0
	v_mov_b32_e32 v6, 0xa100
	global_atomic_add v6, v4, s[98:99]
	s_waitcnt vmcnt(0)
	v_readfirstlane_b32 vcc_lo, v5
	s_add_i32 vcc_lo, vcc_lo, 1
	s_cmp_ge_u32 vcc_lo, vcc_hi
	s_cbranch_scc1 .Lb3_pok_2
	s_movk_i32 m0, 0x3fff
	global_load_dword v5, v3, s[98:99] sc1
	s_sleep 5

.LBB0_866:
	s_getreg_b32 s0, hwreg(HW_REG_XCC_ID, 0, 4)
	s_and_b32 s10, s0, 15
	s_waitcnt vmcnt(0)
	s_waitcnt vmcnt(0)
	s_barrier
	s_and_saveexec_b64 s[0:1], s[52:53]
	v_readlane_b32 s14, v255, 14
	v_readlane_b32 s16, v255, 16
	v_readlane_b32 s15, v255, 15
	v_readlane_b32 s17, v255, 17
	s_add_i32 s101, s101, 1
	s_cbranch_execz .LBB0_918
	v_readlane_b32 s98, v253, 2
	v_readlane_b32 s99, v253, 3
	s_nop 0
	s_add_u32 s98, s98, 0x7c000
	s_addc_u32 s99, s99, 0
	s_and_b32 vcc_lo, s2, 63
	s_lshl_b32 vcc_lo, vcc_lo, 8
	s_add_u32 vcc_lo, vcc_lo, 0x2000
	v_mov_b32_e32 v3, vcc_lo
	v_mov_b32_e32 v4, 1
	s_lshl_b32 vcc_hi, s101, 2
	s_waitcnt vmcnt(0) lgkmcnt(0)
	global_atomic_add v5, v3, v4, s[98:99] sc0
	v_mov_b32_e32 v6, 0xa100
	global_load_dword v7, v6, s[98:99] sc1
	s_waitcnt vmcnt(0)
	v_readfirstlane_b32 vcc_lo, v5
	s_add_i32 vcc_lo, vcc_lo, 1
	s_cmp_ge_u32 vcc_lo, vcc_hi
	s_cbranch_scc1 .Lb3_pok_7
	s_movk_i32 m0, 0x3fff
	global_load_dword v5, v3, s[98:99] sc1
	s_sleep 5

.Lb3_pok_7:
	s_add_i32 vcc_hi, s101, 4
	s_mul_i32 vcc_hi, vcc_hi, 13108
	s_lshr_b32 vcc_hi, vcc_hi, 16
	s_lshr_b32 vcc_hi, vcc_hi, 1
	s_mul_i32 vcc_hi, vcc_hi, s3
	v_readfirstlane_b32 vcc_lo, v7
	s_cmp_ge_u32 vcc_lo, vcc_hi
	s_cbranch_scc1 .Lb3_gok_7
	s_movk_i32 m0, 0x3fff
	global_load_dword v5, v6, s[98:99] sc1
	s_sleep 5
.Lb3_g_7:
	global_load_dword v9, v6, s[98:99] sc1
	s_waitcnt vmcnt(1)
	v_readfirstlane_b32 vcc_lo, v5
	s_cmp_ge_u32 vcc_lo, vcc_hi
	s_cbranch_scc1 .Lb3_gok_7
	global_load_dword v5, v6, s[98:99] sc1
	s_waitcnt vmcnt(1)
	v_readfirstlane_b32 vcc_lo, v9
	s_cmp_ge_u32 vcc_lo, vcc_hi
	s_cbranch_scc1 .Lb3_gok_7
	s_sub_u32 m0, m0, 1
	s_cmp_eq_u32 m0, 0
	s_cbranch_scc0 .Lb3_g_7

.LBB0_954:
	s_getreg_b32 s0, hwreg(HW_REG_XCC_ID, 0, 4)
	s_and_b32 s10, s0, 15
	s_waitcnt vmcnt(0)
	s_barrier
	s_and_saveexec_b64 s[0:1], s[52:53]
	v_readlane_b32 s28, v255, 14
	v_readlane_b32 s14, v255, 16
	v_readlane_b32 s29, v255, 15
	v_readlane_b32 s15, v255, 17
	s_add_i32 s101, s101, 1
	s_cbranch_execz .LBB0_1006
	v_readlane_b32 s98, v253, 2
	v_readlane_b32 s99, v253, 3
	s_nop 0
	s_add_u32 s98, s98, 0x7c000
	s_addc_u32 s99, s99, 0
	s_and_b32 vcc_lo, s2, 63
	s_lshl_b32 vcc_lo, vcc_lo, 8
	s_add_u32 vcc_lo, vcc_lo, 0x2000
	v_mov_b32_e32 v3, vcc_lo
	v_mov_b32_e32 v4, 1
	s_lshl_b32 vcc_hi, s101, 2
	s_waitcnt vmcnt(0) lgkmcnt(0)
	global_atomic_add v5, v3, v4, s[98:99] sc0
	v_mov_b32_e32 v6, 0xa000
	global_atomic_add v6, v4, s[98:99]
	s_waitcnt vmcnt(0)
	v_readfirstlane_b32 vcc_lo, v5
	s_add_i32 vcc_lo, vcc_lo, 1
	s_cmp_ge_u32 vcc_lo, vcc_hi
	s_cbranch_scc1 .Lb3_pok_8
	s_movk_i32 m0, 0x3fff
	global_load_dword v5, v3, s[98:99] sc1
	s_sleep 5

.LBB0_1067:
	s_getreg_b32 s0, hwreg(HW_REG_XCC_ID, 0, 4)
	s_and_b32 s10, s0, 15
	s_waitcnt vmcnt(0)
	s_barrier
	s_and_saveexec_b64 s[0:1], s[52:53]
	v_readlane_b32 s22, v255, 16
	v_readlane_b32 s23, v255, 17
	s_add_i32 s101, s101, 1
	s_cbranch_execz .LBB0_1119
	v_readlane_b32 s98, v253, 2
	v_readlane_b32 s99, v253, 3
	s_nop 0
	s_add_u32 s98, s98, 0x7c000
	s_addc_u32 s99, s99, 0
	s_and_b32 vcc_lo, s2, 63
	s_lshl_b32 vcc_lo, vcc_lo, 8
	s_add_u32 vcc_lo, vcc_lo, 0x2000
	v_mov_b32_e32 v3, vcc_lo
	v_mov_b32_e32 v4, 1
	s_lshl_b32 vcc_hi, s101, 2
	s_waitcnt vmcnt(0) lgkmcnt(0)
	global_atomic_add v5, v3, v4, s[98:99] sc0
	v_mov_b32_e32 v6, 0xa000
	global_load_dword v7, v6, s[98:99] sc1
	s_waitcnt vmcnt(0)
	v_readfirstlane_b32 vcc_lo, v5
	s_add_i32 vcc_lo, vcc_lo, 1
	s_cmp_ge_u32 vcc_lo, vcc_hi
	s_cbranch_scc1 .Lb3_pok_9
	s_movk_i32 m0, 0x3fff
	global_load_dword v5, v3, s[98:99] sc1
	s_sleep 5

.Lb3_pok_9:
	s_add_i32 vcc_hi, s101, 2
	s_mul_i32 vcc_hi, vcc_hi, 13108
	s_lshr_b32 vcc_hi, vcc_hi, 16
	s_mul_i32 vcc_hi, vcc_hi, s3
	v_readfirstlane_b32 vcc_lo, v7
	s_cmp_ge_u32 vcc_lo, vcc_hi
	s_cbranch_scc1 .Lb3_gok_9
	s_movk_i32 m0, 0x3fff
	global_load_dword v5, v6, s[98:99] sc1
	s_sleep 5

.LBB0_1156:
	s_getreg_b32 s0, hwreg(HW_REG_XCC_ID, 0, 4)
	s_and_b32 s4, s0, 15
	s_waitcnt vmcnt(0)
	s_waitcnt vmcnt(0)
	s_barrier
	s_and_saveexec_b64 s[0:1], s[52:53]
	s_add_i32 s101, s101, 1
	s_cbranch_execz .LBB0_1208
	v_readlane_b32 s98, v253, 2
	v_readlane_b32 s99, v253, 3
	s_nop 0
	s_add_u32 s98, s98, 0x7c000
	s_addc_u32 s99, s99, 0
	s_and_b32 vcc_lo, s2, 63
	s_lshl_b32 vcc_lo, vcc_lo, 8
	s_add_u32 vcc_lo, vcc_lo, 0x2000
	v_mov_b32_e32 v3, vcc_lo
	v_mov_b32_e32 v4, 1
	s_lshl_b32 vcc_hi, s101, 2
	s_waitcnt vmcnt(0) lgkmcnt(0)
	global_atomic_add v5, v3, v4, s[98:99] sc0
	s_waitcnt vmcnt(0)
	v_readfirstlane_b32 vcc_lo, v5
	s_add_i32 vcc_lo, vcc_lo, 1
	s_cmp_ge_u32 vcc_lo, vcc_hi
	s_cbranch_scc1 .Lb3_pok_10
	s_movk_i32 m0, 0x3fff
	global_load_dword v5, v3, s[98:99] sc1
	s_sleep 5

.LBB0_1337:
	v_readlane_b32 s34, v255, 14
	v_readlane_b32 s22, v255, 16
	s_and_b64 vcc, exec, s[38:39]
	s_mov_b64 s[0:1], -1
	v_readlane_b32 s35, v255, 15
	v_readlane_b32 s23, v255, 17
	s_cbranch_vccnz .LBB0_1391
	s_getreg_b32 s0, hwreg(HW_REG_XCC_ID, 0, 4)
	s_and_b32 s10, s0, 15
	s_waitcnt vmcnt(0)
	s_barrier
	s_and_saveexec_b64 s[0:1], s[52:53]
	s_add_i32 s101, s101, 1
	s_cbranch_execz .LBB0_1390
	v_readlane_b32 s98, v253, 2
	v_readlane_b32 s99, v253, 3
	s_nop 0
	s_add_u32 s98, s98, 0x7c000
	s_addc_u32 s99, s99, 0
	s_and_b32 vcc_lo, s2, 63
	s_lshl_b32 vcc_lo, vcc_lo, 8
	s_add_u32 vcc_lo, vcc_lo, 0x2000
	v_mov_b32_e32 v3, vcc_lo
	v_mov_b32_e32 v4, 1
	s_lshl_b32 vcc_hi, s101, 2
	s_waitcnt vmcnt(0) lgkmcnt(0)
	global_atomic_add v5, v3, v4, s[98:99] sc0
	s_waitcnt vmcnt(0)
	v_readfirstlane_b32 vcc_lo, v5
	s_add_i32 vcc_lo, vcc_lo, 1
	s_cmp_ge_u32 vcc_lo, vcc_hi
	s_cbranch_scc1 .Lb3_pok_11
	s_movk_i32 m0, 0x3fff
	global_load_dword v5, v3, s[98:99] sc1
	s_sleep 5

.Lb3_pok_11:
	s_mul_i32 vcc_lo, s101, 13108
	s_lshr_b32 vcc_lo, vcc_lo, 16
	s_mul_i32 vcc_hi, vcc_lo, 3
	s_sub_u32 vcc_hi, vcc_hi, 1
	s_lshl_b32 vcc_hi, vcc_hi, 14
	v_readlane_b32 s98, v253, 2
	v_readlane_b32 s99, v253, 3
	s_nop 0
	s_add_u32 s98, s98, 0xc000
	s_addc_u32 s99, s99, 0
	s_add_u32 s98, s98, vcc_hi
	s_addc_u32 s99, s99, 0
	s_and_b32 vcc_lo, vcc_lo, 1
	s_cmp_eq_u32 vcc_lo, 1
	s_cselect_b32 vcc_lo, 12, 14
	s_and_b32 vcc_hi, s2, 7
	s_lshl_b32 vcc_hi, vcc_hi, 3
	s_bfe_u32 m0, s2, 0x30003
	s_add_u32 vcc_hi, vcc_hi, m0
	s_mul_i32 vcc_hi, vcc_hi, vcc_lo
	s_mul_i32 vcc_hi, vcc_hi, 5958
	s_lshr_b32 vcc_hi, vcc_hi, 16
	s_min_u32 vcc_lo, vcc_hi, 63
	s_lshl_b32 vcc_lo, vcc_lo, 8
	v_mov_b32_e32 v6, vcc_lo
	s_add_u32 vcc_hi, vcc_hi, 1
	s_min_u32 vcc_lo, vcc_hi, 63
	s_lshl_b32 vcc_lo, vcc_lo, 8
	v_mov_b32_e32 v7, vcc_lo
	s_add_u32 vcc_hi, vcc_hi, 1
	s_min_u32 vcc_lo, vcc_hi, 63
	s_lshl_b32 vcc_lo, vcc_lo, 8
	v_mov_b32_e32 v8, vcc_lo
	global_load_dword v9, v6, s[98:99] sc1
	global_load_dword v10, v7, s[98:99] sc1
	global_load_dword v11, v8, s[98:99] sc1
	s_mov_b32 vcc_hi, 32
	s_waitcnt vmcnt(0)
	v_min_u32_e32 v9, v9, v10
	v_min_u32_e32 v9, v9, v11
	s_nop 0
	v_readfirstlane_b32 vcc_lo, v9
	s_cmp_ge_u32 vcc_lo, vcc_hi
	s_cbranch_scc1 .Lb3_kok_11
	s_movk_i32 m0, 0x3fff
	global_load_dword v5, v6, s[98:99] sc1
	s_sleep 5

.Lb3_kaok_11:
	s_movk_i32 m0, 0x3fff
	global_load_dword v5, v7, s[98:99] sc1
	s_sleep 5
.Lb3_kb_11:
	global_load_dword v9, v7, s[98:99] sc1
	s_waitcnt vmcnt(1)
	v_readfirstlane_b32 vcc_lo, v5
	s_cmp_ge_u32 vcc_lo, vcc_hi
	s_cbranch_scc1 .Lb3_kbok_11
	global_load_dword v5, v7, s[98:99] sc1
	s_waitcnt vmcnt(1)
	v_readfirstlane_b32 vcc_lo, v9
	s_cmp_ge_u32 vcc_lo, vcc_hi
	s_cbranch_scc1 .Lb3_kbok_11
	s_sub_u32 m0, m0, 1
	s_cmp_eq_u32 m0, 0
	s_cbranch_scc0 .Lb3_kb_11
.Lb3_kbok_11:
	s_movk_i32 m0, 0x3fff
	global_load_dword v5, v8, s[98:99] sc1
	s_sleep 5
.Lb3_kc_11:
	global_load_dword v9, v8, s[98:99] sc1
	s_waitcnt vmcnt(1)
	v_readfirstlane_b32 vcc_lo, v5
	s_cmp_ge_u32 vcc_lo, vcc_hi
	s_cbranch_scc1 .Lb3_kcok_11
	global_load_dword v5, v8, s[98:99] sc1
	s_waitcnt vmcnt(1)
	v_readfirstlane_b32 vcc_lo, v9
	s_cmp_ge_u32 vcc_lo, vcc_hi
	s_cbranch_scc1 .Lb3_kcok_11
	s_sub_u32 m0, m0, 1
	s_cmp_eq_u32 m0, 0
	s_cbranch_scc0 .Lb3_kc_11
